# decode attention items remapped so every workgroup has 4 or 5 cache-row-storing waves (was 2 / 4 / 6)
# baseline (speedup 1.0000x reference)
.LBB0_435:
	v_lshl_or_b32 v2, v0, 3, v121
	v_ashrrev_i32_e32 v126, 2, v2
	v_ashrrev_i32_e32 v127, 31, v126
	v_lshl_add_u64 v[2:3], v[126:127], 4, s[34:35]
	s_waitcnt vmcnt(4)
	v_mov_b32_e32 v125, v1
	v_lshl_add_u64 v[2:3], v[2:3], 0, v[124:125]
	s_waitcnt vmcnt(1)
	v_add_co_u32_e32 v4, vcc, 0x41000, v2
	v_lshlrev_b64 v[8:9], 9, v[126:127]
	s_nop 0
	v_addc_co_u32_e32 v5, vcc, 0, v3, vcc
	v_add_u32_e32 v172, s6, v0
	v_add_co_u32_e32 v6, vcc, 0x82000, v2
	v_or_b32_e32 v8, v8, v123
	v_min_i32_e32 v0, 0x1fff, v172
	v_addc_co_u32_e32 v7, vcc, 0, v3, vcc
	v_lshl_add_u64 v[10:11], s[22:23], 0, v[8:9]
	global_load_dword v204, v[2:3], off
	global_load_dword v177, v[4:5], off
	global_load_dword v176, v[6:7], off
	global_load_dwordx4 v[44:47], v[10:11], off
	v_lshl_add_u64 v[2:3], s[54:55], 0, v[8:9]
	v_lshl_or_b32 v0, v0, 3, v121
	v_lshl_add_u64 v[4:5], s[56:57], 0, v[8:9]
	global_load_dwordx4 v[48:51], v[2:3], off
	global_load_dwordx4 v[40:43], v[4:5], off
	v_ashrrev_i32_e32 v2, 2, v0
	v_ashrrev_i32_e32 v3, 31, v2
	v_lshl_add_u64 v[4:5], v[2:3], 4, s[34:35]
	v_lshl_add_u64 v[4:5], v[4:5], 0, v[124:125]
	s_mov_b32 s14, 0x41000
	v_add_co_u32_e32 v6, vcc, s14, v4
	s_mov_b32 s15, 0x82000
	s_nop 0
	v_addc_co_u32_e32 v7, vcc, 0, v5, vcc
	v_lshlrev_b64 v[2:3], 9, v[2:3]
	v_add_u32_e32 v168, s6, v172
	v_add_co_u32_e32 v8, vcc, s15, v4
	v_or_b32_e32 v2, v2, v123
	v_min_i32_e32 v0, 0x1fff, v168
	v_addc_co_u32_e32 v9, vcc, 0, v5, vcc
	v_lshl_add_u64 v[10:11], s[22:23], 0, v[2:3]
	global_load_dword v175, v[4:5], off
	global_load_dword v174, v[6:7], off
	global_load_dword v173, v[8:9], off
	global_load_dwordx4 v[32:35], v[10:11], off
	v_lshl_add_u64 v[4:5], s[54:55], 0, v[2:3]
	v_lshl_add_u64 v[2:3], s[56:57], 0, v[2:3]
	v_lshl_or_b32 v0, v0, 3, v121
	global_load_dwordx4 v[36:39], v[4:5], off
	global_load_dwordx4 v[28:31], v[2:3], off
	v_ashrrev_i32_e32 v2, 2, v0
	v_ashrrev_i32_e32 v3, 31, v2
	v_lshl_add_u64 v[4:5], v[2:3], 4, s[34:35]
	v_lshl_add_u64 v[4:5], v[4:5], 0, v[124:125]
	v_add_co_u32_e32 v6, vcc, s14, v4
	v_lshlrev_b64 v[2:3], 9, v[2:3]
	s_nop 0
	v_addc_co_u32_e32 v7, vcc, 0, v5, vcc
	v_add_u32_e32 v127, s6, v168
	v_add_co_u32_e32 v8, vcc, s15, v4
	v_or_b32_e32 v2, v2, v123
	v_min_i32_e32 v0, 0x1fff, v127
	v_addc_co_u32_e32 v9, vcc, 0, v5, vcc
	v_lshl_add_u64 v[10:11], s[22:23], 0, v[2:3]
	global_load_dword v171, v[4:5], off
	global_load_dword v170, v[6:7], off
	global_load_dword v169, v[8:9], off
	global_load_dwordx4 v[20:23], v[10:11], off
	v_lshl_add_u64 v[4:5], s[54:55], 0, v[2:3]
	v_lshl_add_u64 v[2:3], s[56:57], 0, v[2:3]
	v_lshl_or_b32 v0, v0, 3, v121
	global_load_dwordx4 v[24:27], v[4:5], off
	global_load_dwordx4 v[16:19], v[2:3], off
	v_ashrrev_i32_e32 v2, 2, v0
	v_ashrrev_i32_e32 v3, 31, v2
	v_lshl_add_u64 v[4:5], v[2:3], 4, s[34:35]
	v_lshl_add_u64 v[4:5], v[4:5], 0, v[124:125]
	v_add_co_u32_e32 v6, vcc, s14, v4
	v_lshlrev_b64 v[2:3], 9, v[2:3]
	s_nop 0
	v_addc_co_u32_e32 v7, vcc, 0, v5, vcc
	v_add_co_u32_e32 v8, vcc, 0x82000, v4
	v_or_b32_e32 v2, v2, v123
	s_nop 0
	v_addc_co_u32_e32 v9, vcc, 0, v5, vcc
	v_lshl_add_u64 v[10:11], s[22:23], 0, v[2:3]
	global_load_dword v131, v[4:5], off
	global_load_dword v129, v[6:7], off
	global_load_dword v125, v[8:9], off
	s_nop 0
	global_load_dwordx4 v[8:11], v[10:11], off
	v_lshl_add_u64 v[4:5], s[54:55], 0, v[2:3]
	v_lshl_add_u64 v[2:3], s[56:57], 0, v[2:3]
	global_load_dwordx4 v[12:15], v[4:5], off
	s_nop 0
	global_load_dwordx4 v[4:7], v[2:3], off
	s_and_b64 vcc, exec, s[24:25]
	s_cbranch_vccnz .LBB0_501
	v_readlane_b32 s14, v251, 40
	v_readlane_b32 s15, v251, 41
	s_mov_b64 s[24:25], -1
	s_and_b64 vcc, exec, s[14:15]
	s_cbranch_vccz .LBB0_497
	v_readlane_b32 s14, v251, 42
	v_readlane_b32 s15, v251, 43
	s_and_b64 vcc, exec, s[14:15]
	s_cbranch_vccz .LBB0_492
	v_mov_b32_e32 v0, v178
	v_readlane_b32 s14, v251, 44
	v_ashrrev_i32_e32 v2, 6, v0
	s_nop 0
	v_add_u32_e32 v205, s14, v2
	s_movk_i32 s14, 0x600
	v_cmp_gt_i32_e32 vcc, s14, v205
	s_and_saveexec_b64 s[74:75], vcc
	s_cbranch_execz .LBB0_470
	v_readfirstlane_b32 s28, v205
	s_and_b32 s29, s28, 7
	s_lshr_b32 s28, s28, 3
	s_and_b32 s30, s29, 1
	s_lshr_b32 s29, s29, 1
	s_mul_hi_u32 s31, s28, 0x2aaaaaab
	s_mul_i32 s14, s31, 6
	s_sub_i32 s28, s28, s14
	s_mul_i32 s15, s30, 3
	s_lshl_b32 s20, s28, 1
	s_mov_b32 s21, s20
	s_mov_b32 vcc_lo, 2
	s_cmp_eq_u32 s28, s15
	s_cselect_b32 vcc_lo, 3, vcc_lo
	s_cmp_gt_u32 s28, s15
	s_cselect_b32 s14, 1, 0
	s_add_i32 s20, s20, s14
	s_sub_i32 s21, s21, s14
	s_cmp_lt_u32 s29, vcc_lo
	s_cbranch_scc0 .Lrm_non
	s_mul_i32 s14, s31, 13
	s_add_i32 s14, s14, s20
	s_add_i32 s14, s14, s29
	s_cmpk_lt_u32 s14, 0x100
	s_cbranch_scc0 .Lrm_s1
	s_mov_b32 vcc_hi, 2
	s_mov_b32 s28, s14
	s_branch .Lrm_join
.Lrm_s1:
	s_cmpk_lt_u32 s14, 0x180
	s_cbranch_scc0 .Lrm_s0
	s_addk_i32 s14, 0xff00
	s_lshr_b32 s28, s14, 2
	s_lshl_b32 s28, s28, 3
	s_and_b32 s14, s14, 3
	s_add_i32 s28, s28, s14
	s_mov_b32 vcc_hi, 1
	s_branch .Lrm_join
.Lrm_s0:
	s_addk_i32 s14, 0xfe80
	s_lshl_b32 s28, s14, 3
	s_mov_b32 vcc_hi, 0
	s_branch .Lrm_join
.Lrm_non:
	s_mul_i32 s14, s31, 11
	s_add_i32 s14, s14, s21
	s_add_i32 s14, s14, s29
	s_sub_i32 s14, s14, vcc_lo
	s_cmpk_lt_u32 s14, 0x80
	s_cbranch_scc0 .Lrm_n0
	s_lshr_b32 s28, s14, 2
	s_lshl_b32 s28, s28, 3
	s_and_b32 s14, s14, 3
	s_add_i32 s28, s28, s14
	s_add_i32 s28, s28, 4
	s_mov_b32 vcc_hi, 1
	s_branch .Lrm_join
.Lrm_n0:
	s_addk_i32 s14, 0xff80
	s_mul_hi_u32 s15, s14, 0x24924925
	s_mul_i32 s20, s15, 7
	s_sub_i32 s14, s14, s20
	s_lshl_b32 s28, s15, 3
	s_add_i32 s28, s28, s14
	s_add_i32 s28, s28, 1
	s_mov_b32 vcc_hi, 0
.Lrm_join:
	s_mul_i32 s28, s28, 6
	s_lshl_b32 vcc_hi, vcc_hi, 1
	s_add_i32 s28, s28, vcc_hi
	s_add_i32 s28, s28, s30
	v_mov_b32_e32 v205, s28
	v_bfe_u32 v52, v0, 4, 2
	v_and_b32_e32 v2, 15, v0
	v_bfe_u32 v0, v0, 6, 1
	v_cmp_eq_u32_e64 s[46:47], 0, v0
	v_mov_b32_e32 v3, 0x81
	v_mov_b32_e32 v53, 0x41
	v_readlane_b32 s14, v255, 7
	v_lshlrev_b32_e32 v130, 2, v2
	v_cmp_eq_u32_e64 s[44:45], 0, v2
	v_cndmask_b32_e64 v206, v3, v53, s[46:47]
	v_mul_u32_u24_e32 v132, 3, v0
	v_lshlrev_b32_e32 v0, 3, v2
	v_lshlrev_b32_e32 v2, 7, v52
	v_mov_b32_e32 v3, v1
	v_readlane_b32 s15, v255, 8
	v_lshl_add_u64 v[134:135], s[18:19], 0, v[0:1]
	v_lshlrev_b32_e32 v128, 6, v52
	v_lshl_add_u64 v[2:3], s[14:15], 0, v[2:3]
	v_readlane_b32 s14, v255, 9
	v_lshl_add_u64 v[136:137], v[2:3], 0, v[0:1]
	v_lshlrev_b32_e32 v0, 2, v52
	v_readlane_b32 s15, v255, 10
	v_add_u32_e32 v207, -1, v206
	v_mov_b32_e32 v133, v1
	v_lshl_add_u64 v[138:139], s[14:15], 0, v[0:1]
	s_mov_b64 s[58:59], 0
	v_lshlrev_b32_e32 v140, 1, v130
	s_branch .LBB0_441
